# weight conversion moved into the idle workgroups of the last round of the proj and gate/up GEMMs (phase 0 only converts layer 0's W_in/W_out/LRU weights)
# speedup vs baseline: 1.0185x; 1.0185x over previous
; __device__ __forceinline__ WDesc wdesc(const Params& p, int l, int u) {
;     unsigned char* ws = p.ws;
;     constexpr int T_IN = 44 * 16, T_OUT = 16 * 16, T_GU = 88 * 16, T_D = 16 * 44;
;     WDesc d; int v = u;
;     if (v < T_IN) { const int rt = v / 16, kt = v % 16; int nv = DIN - rt * 64; nv = nv > 64 ? 64 : (nv < 0 ? 0 : nv);
;         d.src = p.in[3] + (size_t)l * D * DIN; d.ldsrc = DIN; d.c0 = nv > 0 ? rt * 64 : 0; d.nvalid = nv; d.k0 = kt * 64; d.dst = (bf16_t*)(ws + WS_WIN); d.lddst = D; d.r0 = rt * 64; return d; }
;     v -= T_IN;
;     if (v < T_OUT) { const int rt = v / 16, kt = v % 16; d.src = p.in[15] + (size_t)l * D * D; d.ldsrc = D; d.c0 = rt * 64; d.nvalid = 64; d.k0 = kt * 64; d.dst = (bf16_t*)(ws + WS_WOUT); d.lddst = D; d.r0 = rt * 64; return d; }
;     v -= T_OUT;
;     if (v < T_GU) { const int rt = v / 16, kt = v % 16; const int r0 = rt * 64, j = r0 / 256, within = r0 % 256;
;         d.src = (within < 128 ? p.in[18] : p.in[19]) + (size_t)l * D * DFF; d.ldsrc = DFF; d.c0 = j * 128 + (within & 127); d.nvalid = 64; d.k0 = kt * 64; d.dst = (bf16_t*)(ws + WS_WGU); d.lddst = D; d.r0 = r0; return d; }
;     v -= T_GU;
;     if (v < T_D) { const int rt = v / 44, kt = v % 44; d.src = p.in[20] + (size_t)l * DFF * D; d.ldsrc = D; d.c0 = rt * 64; d.nvalid = 64; d.k0 = kt * 64; d.dst = (bf16_t*)(ws + WS_WD); d.lddst = DFF; d.r0 = rt * 64; return d; }
;     v -= T_D;
;     { const int dir = v / 16, gate = (v / 8) % 2, h = v % 8; d.src = (gate ? p.in[8] : p.in[6]) + ((size_t)(l * 2 + dir) * 8 + h) * 4096; d.ldsrc = 64; d.c0 = 0; d.nvalid = 64; d.k0 = 0;
;       d.dst = (bf16_t*)(ws + WS_LRUW) + ((size_t)(dir * 2 + gate) * 8 + h) * 4096; d.lddst = 64; d.r0 = 0; return d; }
; __device__ void phase_weights(const Params& p, int l, LAS unsigned char* lds) {
;     LAS float* T = (LAS float*)lds;
;     unsigned char* ws = p.ws;
;     constexpr int TOT = 44 * 16 + 16 * 16 + 88 * 16 + 16 * 44 + 32;
;     const int tid = otid(), G = gridDim.x;
;     for (int u0 = obid(); u0 < TOT; u0 += 4 * G) {
;         f32x4 v[4][2];
;         { const int k = tid >> 3, cg8 = (tid & 7) * 8;
; #pragma unroll
;           for (int j = 0; j < 4; ++j) { const int u = u0 + j * G; v[j][0] = (f32x4){0.f, 0.f, 0.f, 0.f}; v[j][1] = v[j][0];
;               if (u < TOT) { const WDesc d = wdesc(p, l, u); const float* sp = d.src + (size_t)(d.k0 + k) * d.ldsrc + d.c0 + cg8;
.LBB0_119:
	s_mov_b64 s[0:1], -1
	s_waitcnt vmcnt(0) lgkmcnt(0)
	s_barrier
	v_writelane_b32 v100, s0, 0
	v_writelane_b32 v100, s1, 1
	v_writelane_b32 v100, s4, 2
	v_writelane_b32 v100, s5, 3
	v_writelane_b32 v100, s6, 4
	v_writelane_b32 v100, s7, 5
	v_writelane_b32 v100, s8, 6
	v_writelane_b32 v100, s9, 7
	v_writelane_b32 v100, s10, 8
	v_writelane_b32 v100, s11, 9
	v_writelane_b32 v100, s12, 10
	v_writelane_b32 v100, s13, 11
	v_writelane_b32 v100, s14, 12
	v_writelane_b32 v100, s15, 13
	v_writelane_b32 v100, s16, 14
	v_writelane_b32 v100, s17, 15
	v_writelane_b32 v100, s18, 16
	v_writelane_b32 v100, s19, 17
	v_writelane_b32 v100, s20, 18
	v_writelane_b32 v100, s21, 19
	v_writelane_b32 v100, s27, 20
	v_writelane_b32 v100, s30, 21
	v_writelane_b32 v100, s31, 22
	v_writelane_b32 v100, s34, 23
	v_writelane_b32 v100, s38, 24
	v_writelane_b32 v100, s39, 25
	v_writelane_b32 v100, s40, 26
	v_writelane_b32 v100, s41, 27
	v_writelane_b32 v100, s43, 28
	v_writelane_b32 v100, s44, 29
	v_writelane_b32 v100, s45, 30
	v_writelane_b32 v100, s46, 31
	v_writelane_b32 v100, s47, 32
	v_writelane_b32 v100, s48, 33
	v_writelane_b32 v100, s51, 34
	v_readlane_b32 s21, v254, 59
	v_readlane_b32 s51, v255, 16
	v_readfirstlane_b32 s20, v245
	s_nop 1
	s_cmpk_lt_u32 s21, 0x80
	s_cbranch_scc1 .Lwp7_done
	s_sub_u32 s21, s21, 0x80
	s_add_u32 s51, s51, 1
	s_cmp_gt_u32 s51, 3
	s_cbranch_scc1 .Lwp7_done
	v_and_b32_e32 v0, 63, v245
	v_readlane_b32 s4, v254, 33
	v_readlane_b32 s5, v254, 34
	v_readlane_b32 s6, v254, 57
	v_readlane_b32 s7, v254, 58
	v_readlane_b32 s8, v253, 4
	v_readlane_b32 s9, v253, 5
	v_readlane_b32 s10, v253, 6
	v_readlane_b32 s11, v253, 7
	v_readlane_b32 s12, v254, 60
	v_readlane_b32 s13, v254, 61
	v_readlane_b32 s14, v254, 39
	v_readlane_b32 s15, v254, 40
	v_readlane_b32 s16, v254, 43
	v_readlane_b32 s17, v254, 44
	v_readlane_b32 s18, v255, 0
	v_readlane_b32 s19, v255, 1
	s_lshr_b32 s20, s20, 6
	s_lshl_b32 s31, s20, 14
	s_mul_i32 s0, s51, 0xa20000
	s_add_u32 s4, s4, s0
	s_addc_u32 s5, s5, 0
	s_lshl_b32 s0, s51, 22
	s_add_u32 s6, s6, s0
	s_addc_u32 s7, s7, 0
	s_mul_i32 s0, s51, 0xb00000
	s_add_u32 s8, s8, s0
	s_addc_u32 s9, s9, 0
	s_add_u32 s10, s10, s0
	s_addc_u32 s11, s11, 0
	s_add_u32 s12, s12, s0
	s_addc_u32 s13, s13, 0
	s_lshl_b32 s0, s51, 18
	s_add_u32 s14, s14, s0
	s_addc_u32 s15, s15, 0
	s_add_u32 s16, s16, s0
	s_addc_u32 s17, s17, 0
	v_lshrrev_b32_e32 v1, 4, v0
	v_and_b32_e32 v22, 15, v0
	v_xor_b32_e32 v2, 0, v22
	v_lshlrev_b32_e32 v2, 4, v2
	v_xor_b32_e32 v3, 1, v22
	v_lshlrev_b32_e32 v3, 4, v3
	v_xor_b32_e32 v4, 2, v22
	v_lshlrev_b32_e32 v4, 4, v4
	v_xor_b32_e32 v5, 3, v22
	v_lshlrev_b32_e32 v5, 4, v5
	v_xor_b32_e32 v6, 4, v22
	v_lshlrev_b32_e32 v6, 4, v6
	v_xor_b32_e32 v7, 5, v22
	v_lshlrev_b32_e32 v7, 4, v7
	v_xor_b32_e32 v8, 6, v22
	v_lshlrev_b32_e32 v8, 4, v8
	v_xor_b32_e32 v9, 7, v22
	v_lshlrev_b32_e32 v9, 4, v9
	v_lshrrev_b32_e32 v10, 3, v0
	v_and_b32_e32 v11, 7, v0
	v_lshrrev_b32_e32 v22, 2, v10
	v_and_b32_e32 v23, 3, v10
	v_lshlrev_b32_e32 v23, 2, v23
	v_lshl_add_u32 v23, v11, 11, v23
	v_add_u32_e32 v23, s31, v23
	v_add_u32_e32 v12, 0, v22
	v_xor_b32_e32 v12, v12, v11
	v_lshl_add_u32 v12, v12, 4, v23
	v_add_u32_e32 v13, 2, v22
	v_xor_b32_e32 v13, v13, v11
	v_lshl_add_u32 v13, v13, 4, v23
	v_add_u32_e32 v14, 4, v22
	v_xor_b32_e32 v14, v14, v11
	v_lshl_add_u32 v14, v14, 4, v23
	v_add_u32_e32 v15, 6, v22
	v_xor_b32_e32 v15, v15, v11
	v_lshl_add_u32 v15, v15, 4, v23
	v_add_u32_e32 v16, 8, v22
	v_xor_b32_e32 v16, v16, v11
	v_lshl_add_u32 v16, v16, 4, v23
	v_add_u32_e32 v17, 10, v22
	v_xor_b32_e32 v17, v17, v11
	v_lshl_add_u32 v17, v17, 4, v23
	v_add_u32_e32 v18, 12, v22
	v_xor_b32_e32 v18, v18, v11
	v_lshl_add_u32 v18, v18, 4, v23
	v_add_u32_e32 v19, 14, v22
	v_xor_b32_e32 v19, v19, v11
	v_lshl_add_u32 v19, v19, 4, v23
	s_mul_i32 s27, s20, 128
	s_add_u32 s27, s27, s21
.Lwp7_round:
	s_cmpk_ge_u32 s27, 0x3e0
	s_cbranch_scc1 .Lwp7_done
	s_mov_b32 s30, s27
	s_cmpk_lt_u32 s27, 0x3c0
	s_cbranch_scc1 .Lwp7_decode
	s_add_u32 s30, s27, 0x840

; #define LAS __attribute__((address_space(3)))
; __device__ __forceinline__ unsigned cvtpk(float lo, float hi) { const f32x2 v = (f32x2){lo, hi}; const bf16v2 b = __builtin_convertvector(v, bf16v2); return __builtin_bit_cast(unsigned, b); }
; __device__ void phase_weights(const Params& p, int l, LAS unsigned char* lds) {
;     ...
;         { const int r = tid >> 3, kg = (tid & 7) * 8;
; #pragma unroll
;           for (int j = 0; j < 4; ++j) { const int u = u0 + j * G;
;               if (u < TOT) { const WDesc d = wdesc(p, l, u); const LAS float* Tj = T + j * 4160; u32x4 w;
;                   w.x = cvtpk(Tj[(kg + 0) * 65 + r], Tj[(kg + 1) * 65 + r]); w.y = cvtpk(Tj[(kg + 2) * 65 + r], Tj[(kg + 3) * 65 + r]);
;                   w.z = cvtpk(Tj[(kg + 4) * 65 + r], Tj[(kg + 5) * 65 + r]); w.w = cvtpk(Tj[(kg + 6) * 65 + r], Tj[(kg + 7) * 65 + r]);
;                   *(u32x4*)(d.dst + (size_t)(d.r0 + r) * d.lddst + d.k0 + kg) = w; } } }
;         __syncthreads();
;     }
.Lwp7_s7:
	global_store_dwordx4 v21, v[44:47], s[44:45]
	s_add_u32 s27, s27, 0x400
	s_branch .Lwp7_round
.Lwp7_done:
	s_waitcnt lgkmcnt(0)
	v_readlane_b32 s0, v100, 0
	v_readlane_b32 s1, v100, 1
	v_readlane_b32 s4, v100, 2
	v_readlane_b32 s5, v100, 3
	v_readlane_b32 s6, v100, 4
	v_readlane_b32 s7, v100, 5
	v_readlane_b32 s8, v100, 6
	v_readlane_b32 s9, v100, 7
	v_readlane_b32 s10, v100, 8
	v_readlane_b32 s11, v100, 9
	v_readlane_b32 s12, v100, 10
	v_readlane_b32 s13, v100, 11
	v_readlane_b32 s14, v100, 12
	v_readlane_b32 s15, v100, 13
	v_readlane_b32 s16, v100, 14
	v_readlane_b32 s17, v100, 15
	v_readlane_b32 s18, v100, 16
	v_readlane_b32 s19, v100, 17
	v_readlane_b32 s20, v100, 18
	v_readlane_b32 s21, v100, 19
	v_readlane_b32 s27, v100, 20
	v_readlane_b32 s30, v100, 21
	v_readlane_b32 s31, v100, 22
	v_readlane_b32 s34, v100, 23
	v_readlane_b32 s38, v100, 24
	v_readlane_b32 s39, v100, 25
	v_readlane_b32 s40, v100, 26
	v_readlane_b32 s41, v100, 27
	v_readlane_b32 s43, v100, 28
	v_readlane_b32 s44, v100, 29
	v_readlane_b32 s45, v100, 30
	v_readlane_b32 s46, v100, 31
	v_readlane_b32 s47, v100, 32
	v_readlane_b32 s48, v100, 33
	v_readlane_b32 s51, v100, 34
	s_nop 4

; __device__ __forceinline__ WDesc wdesc(const Params& p, int l, int u) {
;     unsigned char* ws = p.ws;
;     constexpr int T_IN = 44 * 16, T_OUT = 16 * 16, T_GU = 88 * 16, T_D = 16 * 44;
;     WDesc d; int v = u;
;     if (v < T_IN) { const int rt = v / 16, kt = v % 16; int nv = DIN - rt * 64; nv = nv > 64 ? 64 : (nv < 0 ? 0 : nv);
;         d.src = p.in[3] + (size_t)l * D * DIN; d.ldsrc = DIN; d.c0 = nv > 0 ? rt * 64 : 0; d.nvalid = nv; d.k0 = kt * 64; d.dst = (bf16_t*)(ws + WS_WIN); d.lddst = D; d.r0 = rt * 64; return d; }
;     v -= T_IN;
;     if (v < T_OUT) { const int rt = v / 16, kt = v % 16; d.src = p.in[15] + (size_t)l * D * D; d.ldsrc = D; d.c0 = rt * 64; d.nvalid = 64; d.k0 = kt * 64; d.dst = (bf16_t*)(ws + WS_WOUT); d.lddst = D; d.r0 = rt * 64; return d; }
;     v -= T_OUT;
;     if (v < T_GU) { const int rt = v / 16, kt = v % 16; const int r0 = rt * 64, j = r0 / 256, within = r0 % 256;
;         d.src = (within < 128 ? p.in[18] : p.in[19]) + (size_t)l * D * DFF; d.ldsrc = DFF; d.c0 = j * 128 + (within & 127); d.nvalid = 64; d.k0 = kt * 64; d.dst = (bf16_t*)(ws + WS_WGU); d.lddst = D; d.r0 = r0; return d; }
;     v -= T_GU;
;     if (v < T_D) { const int rt = v / 44, kt = v % 44; d.src = p.in[20] + (size_t)l * DFF * D; d.ldsrc = D; d.c0 = rt * 64; d.nvalid = 64; d.k0 = kt * 64; d.dst = (bf16_t*)(ws + WS_WD); d.lddst = DFF; d.r0 = rt * 64; return d; }
;     v -= T_D;
;     { const int dir = v / 16, gate = (v / 8) % 2, h = v % 8; d.src = (gate ? p.in[8] : p.in[6]) + ((size_t)(l * 2 + dir) * 8 + h) * 4096; d.ldsrc = 64; d.c0 = 0; d.nvalid = 64; d.k0 = 0;
;       d.dst = (bf16_t*)(ws + WS_LRUW) + ((size_t)(dir * 2 + gate) * 8 + h) * 4096; d.lddst = 64; d.r0 = 0; return d; }
; __device__ void phase_weights(const Params& p, int l, LAS unsigned char* lds) {
;     LAS float* T = (LAS float*)lds;
;     unsigned char* ws = p.ws;
;     constexpr int TOT = 44 * 16 + 16 * 16 + 88 * 16 + 16 * 44 + 32;
;     const int tid = otid(), G = gridDim.x;
;     for (int u0 = obid(); u0 < TOT; u0 += 4 * G) {
;         f32x4 v[4][2];
;         { const int k = tid >> 3, cg8 = (tid & 7) * 8;
; #pragma unroll
;           for (int j = 0; j < 4; ++j) { const int u = u0 + j * G; v[j][0] = (f32x4){0.f, 0.f, 0.f, 0.f}; v[j][1] = v[j][0];
;               if (u < TOT) { const WDesc d = wdesc(p, l, u); const float* sp = d.src + (size_t)(d.k0 + k) * d.ldsrc + d.c0 + cg8;
.LBB0_363:
	s_waitcnt vmcnt(0) lgkmcnt(0)
	s_barrier
	v_writelane_b32 v100, s0, 0
	v_writelane_b32 v100, s1, 1
	v_writelane_b32 v100, s4, 2
	v_writelane_b32 v100, s5, 3
	v_writelane_b32 v100, s6, 4
	v_writelane_b32 v100, s7, 5
	v_writelane_b32 v100, s8, 6
	v_writelane_b32 v100, s9, 7
	v_writelane_b32 v100, s10, 8
	v_writelane_b32 v100, s11, 9
	v_writelane_b32 v100, s12, 10
	v_writelane_b32 v100, s13, 11
	v_writelane_b32 v100, s14, 12
	v_writelane_b32 v100, s15, 13
	v_writelane_b32 v100, s16, 14
	v_writelane_b32 v100, s17, 15
	v_writelane_b32 v100, s18, 16
	v_writelane_b32 v100, s19, 17
	v_writelane_b32 v100, s20, 18
	v_writelane_b32 v100, s21, 19
	v_writelane_b32 v100, s27, 20
	v_writelane_b32 v100, s30, 21
	v_writelane_b32 v100, s31, 22
	v_writelane_b32 v100, s34, 23
	v_writelane_b32 v100, s38, 24
	v_writelane_b32 v100, s39, 25
	v_writelane_b32 v100, s40, 26
	v_writelane_b32 v100, s41, 27
	v_writelane_b32 v100, s43, 28
	v_writelane_b32 v100, s44, 29
	v_writelane_b32 v100, s45, 30
	v_writelane_b32 v100, s46, 31
	v_writelane_b32 v100, s47, 32
	v_writelane_b32 v100, s48, 33
	v_writelane_b32 v100, s51, 34
	v_readlane_b32 s21, v254, 59
	v_readlane_b32 s51, v255, 16
	v_readfirstlane_b32 s20, v245
	s_nop 1
	s_cmpk_lt_u32 s21, 0xc0
	s_cbranch_scc1 .Lwp1_done
	s_sub_u32 s21, s21, 0xc0
	v_and_b32_e32 v0, 63, v245
	v_readlane_b32 s4, v254, 33
	v_readlane_b32 s5, v254, 34
	v_readlane_b32 s6, v254, 57
	v_readlane_b32 s7, v254, 58
	v_readlane_b32 s8, v253, 4
	v_readlane_b32 s9, v253, 5
	v_readlane_b32 s10, v253, 6
	v_readlane_b32 s11, v253, 7
	v_readlane_b32 s12, v254, 60
	v_readlane_b32 s13, v254, 61
	v_readlane_b32 s14, v254, 39
	v_readlane_b32 s15, v254, 40
	v_readlane_b32 s16, v254, 43
	v_readlane_b32 s17, v254, 44
	v_readlane_b32 s18, v255, 0
	v_readlane_b32 s19, v255, 1
	s_lshr_b32 s20, s20, 6
	s_lshl_b32 s31, s20, 14
	s_mul_i32 s0, s51, 0xa20000
	s_add_u32 s4, s4, s0
	s_addc_u32 s5, s5, 0
	s_lshl_b32 s0, s51, 22
	s_add_u32 s6, s6, s0
	s_addc_u32 s7, s7, 0
	s_mul_i32 s0, s51, 0xb00000
	s_add_u32 s8, s8, s0
	s_addc_u32 s9, s9, 0
	s_add_u32 s10, s10, s0
	s_addc_u32 s11, s11, 0
	s_add_u32 s12, s12, s0
	s_addc_u32 s13, s13, 0
	s_lshl_b32 s0, s51, 18
	s_add_u32 s14, s14, s0
	s_addc_u32 s15, s15, 0
	s_add_u32 s16, s16, s0
	s_addc_u32 s17, s17, 0
	v_lshrrev_b32_e32 v1, 4, v0
	v_and_b32_e32 v22, 15, v0
	v_xor_b32_e32 v2, 0, v22
	v_lshlrev_b32_e32 v2, 4, v2
	v_xor_b32_e32 v3, 1, v22
	v_lshlrev_b32_e32 v3, 4, v3
	v_xor_b32_e32 v4, 2, v22
	v_lshlrev_b32_e32 v4, 4, v4
	v_xor_b32_e32 v5, 3, v22
	v_lshlrev_b32_e32 v5, 4, v5
	v_xor_b32_e32 v6, 4, v22
	v_lshlrev_b32_e32 v6, 4, v6
	v_xor_b32_e32 v7, 5, v22
	v_lshlrev_b32_e32 v7, 4, v7
	v_xor_b32_e32 v8, 6, v22
	v_lshlrev_b32_e32 v8, 4, v8
	v_xor_b32_e32 v9, 7, v22
	v_lshlrev_b32_e32 v9, 4, v9
	v_lshrrev_b32_e32 v10, 3, v0
	v_and_b32_e32 v11, 7, v0
	v_lshrrev_b32_e32 v22, 2, v10
	v_and_b32_e32 v23, 3, v10
	v_lshlrev_b32_e32 v23, 2, v23
	v_lshl_add_u32 v23, v11, 11, v23
	v_add_u32_e32 v23, s31, v23
	v_add_u32_e32 v12, 0, v22
	v_xor_b32_e32 v12, v12, v11
	v_lshl_add_u32 v12, v12, 4, v23
	v_add_u32_e32 v13, 2, v22
	v_xor_b32_e32 v13, v13, v11
	v_lshl_add_u32 v13, v13, 4, v23
	v_add_u32_e32 v14, 4, v22
	v_xor_b32_e32 v14, v14, v11
	v_lshl_add_u32 v14, v14, 4, v23
	v_add_u32_e32 v15, 6, v22
	v_xor_b32_e32 v15, v15, v11
	v_lshl_add_u32 v15, v15, 4, v23
	v_add_u32_e32 v16, 8, v22
	v_xor_b32_e32 v16, v16, v11
	v_lshl_add_u32 v16, v16, 4, v23
	v_add_u32_e32 v17, 10, v22
	v_xor_b32_e32 v17, v17, v11
	v_lshl_add_u32 v17, v17, 4, v23
	v_add_u32_e32 v18, 12, v22
	v_xor_b32_e32 v18, v18, v11
	v_lshl_add_u32 v18, v18, 4, v23
	v_add_u32_e32 v19, 14, v22
	v_xor_b32_e32 v19, v19, v11
	v_lshl_add_u32 v19, v19, 4, v23
	s_mul_i32 s27, s20, 64
	s_add_u32 s27, s27, s21
.Lwp1_round:
	s_cmpk_ge_u32 s27, 0x840
	s_cbranch_scc1 .Lwp1_done
	s_add_u32 s30, s27, 0x3c0

; #define LAS __attribute__((address_space(3)))
; __device__ __forceinline__ unsigned cvtpk(float lo, float hi) { const f32x2 v = (f32x2){lo, hi}; const bf16v2 b = __builtin_convertvector(v, bf16v2); return __builtin_bit_cast(unsigned, b); }
; __device__ void phase_weights(const Params& p, int l, LAS unsigned char* lds) {
;     ...
;         { const int r = tid >> 3, kg = (tid & 7) * 8;
; #pragma unroll
;           for (int j = 0; j < 4; ++j) { const int u = u0 + j * G;
;               if (u < TOT) { const WDesc d = wdesc(p, l, u); const LAS float* Tj = T + j * 4160; u32x4 w;
;                   w.x = cvtpk(Tj[(kg + 0) * 65 + r], Tj[(kg + 1) * 65 + r]); w.y = cvtpk(Tj[(kg + 2) * 65 + r], Tj[(kg + 3) * 65 + r]);
;                   w.z = cvtpk(Tj[(kg + 4) * 65 + r], Tj[(kg + 5) * 65 + r]); w.w = cvtpk(Tj[(kg + 6) * 65 + r], Tj[(kg + 7) * 65 + r]);
;                   *(u32x4*)(d.dst + (size_t)(d.r0 + r) * d.lddst + d.k0 + kg) = w; } } }
;         __syncthreads();
;     }
.Lwp1_s7:
	global_store_dwordx4 v21, v[44:47], s[44:45]
	s_add_u32 s27, s27, 0x200
	s_branch .Lwp1_round
.Lwp1_done:
	s_waitcnt lgkmcnt(0)
	v_readlane_b32 s0, v100, 0
	v_readlane_b32 s1, v100, 1
	v_readlane_b32 s4, v100, 2
	v_readlane_b32 s5, v100, 3
	v_readlane_b32 s6, v100, 4
	v_readlane_b32 s7, v100, 5
	v_readlane_b32 s8, v100, 6
	v_readlane_b32 s9, v100, 7
	v_readlane_b32 s10, v100, 8
	v_readlane_b32 s11, v100, 9
	v_readlane_b32 s12, v100, 10
	v_readlane_b32 s13, v100, 11
	v_readlane_b32 s14, v100, 12
	v_readlane_b32 s15, v100, 13
	v_readlane_b32 s16, v100, 14
	v_readlane_b32 s17, v100, 15
	v_readlane_b32 s18, v100, 16
	v_readlane_b32 s19, v100, 17
	v_readlane_b32 s20, v100, 18
	v_readlane_b32 s21, v100, 19
	v_readlane_b32 s27, v100, 20
	v_readlane_b32 s30, v100, 21
	v_readlane_b32 s31, v100, 22
	v_readlane_b32 s34, v100, 23
	v_readlane_b32 s38, v100, 24
	v_readlane_b32 s39, v100, 25
	v_readlane_b32 s40, v100, 26
	v_readlane_b32 s41, v100, 27
	v_readlane_b32 s43, v100, 28
	v_readlane_b32 s44, v100, 29
	v_readlane_b32 s45, v100, 30
	v_readlane_b32 s46, v100, 31
	v_readlane_b32 s47, v100, 32
	v_readlane_b32 s48, v100, 33
	v_readlane_b32 s51, v100, 34
	s_nop 4
	s_mov_b64 s[0:1], -1
	s_branch .LBB0_347

; __device__ __forceinline__ WDesc wdesc(const Params& p, int l, int u) {
;     unsigned char* ws = p.ws;
;     constexpr int T_IN = 44 * 16, T_OUT = 16 * 16, T_GU = 88 * 16, T_D = 16 * 44;
;     WDesc d; int v = u;
;     if (v < T_IN) { const int rt = v / 16, kt = v % 16; int nv = DIN - rt * 64; nv = nv > 64 ? 64 : (nv < 0 ? 0 : nv);
;         d.src = p.in[3] + (size_t)l * D * DIN; d.ldsrc = DIN; d.c0 = nv > 0 ? rt * 64 : 0; d.nvalid = nv; d.k0 = kt * 64; d.dst = (bf16_t*)(ws + WS_WIN); d.lddst = D; d.r0 = rt * 64; return d; }
;     v -= T_IN;
;     if (v < T_OUT) { const int rt = v / 16, kt = v % 16; d.src = p.in[15] + (size_t)l * D * D; d.ldsrc = D; d.c0 = rt * 64; d.nvalid = 64; d.k0 = kt * 64; d.dst = (bf16_t*)(ws + WS_WOUT); d.lddst = D; d.r0 = rt * 64; return d; }
;     v -= T_OUT;
;     if (v < T_GU) { const int rt = v / 16, kt = v % 16; const int r0 = rt * 64, j = r0 / 256, within = r0 % 256;
;         d.src = (within < 128 ? p.in[18] : p.in[19]) + (size_t)l * D * DFF; d.ldsrc = DFF; d.c0 = j * 128 + (within & 127); d.nvalid = 64; d.k0 = kt * 64; d.dst = (bf16_t*)(ws + WS_WGU); d.lddst = D; d.r0 = r0; return d; }
;     v -= T_GU;
;     if (v < T_D) { const int rt = v / 44, kt = v % 44; d.src = p.in[20] + (size_t)l * DFF * D; d.ldsrc = D; d.c0 = rt * 64; d.nvalid = 64; d.k0 = kt * 64; d.dst = (bf16_t*)(ws + WS_WD); d.lddst = DFF; d.r0 = rt * 64; return d; }
;     v -= T_D;
;     { const int dir = v / 16, gate = (v / 8) % 2, h = v % 8; d.src = (gate ? p.in[8] : p.in[6]) + ((size_t)(l * 2 + dir) * 8 + h) * 4096; d.ldsrc = 64; d.c0 = 0; d.nvalid = 64; d.k0 = 0;
;       d.dst = (bf16_t*)(ws + WS_LRUW) + ((size_t)(dir * 2 + gate) * 8 + h) * 4096; d.lddst = 64; d.r0 = 0; return d; }
; __device__ void phase_weights(const Params& p, int l, LAS unsigned char* lds) {
;     LAS float* T = (LAS float*)lds;
;     unsigned char* ws = p.ws;
;     constexpr int TOT = 44 * 16 + 16 * 16 + 88 * 16 + 16 * 44 + 32;
;     const int tid = otid(), G = gridDim.x;
;     for (int u0 = obid(); u0 < TOT; u0 += 4 * G) {
;         f32x4 v[4][2];
;         { const int k = tid >> 3, cg8 = (tid & 7) * 8;
; #pragma unroll
;           for (int j = 0; j < 4; ++j) { const int u = u0 + j * G; v[j][0] = (f32x4){0.f, 0.f, 0.f, 0.f}; v[j][1] = v[j][0];
;               if (u < TOT) { const WDesc d = wdesc(p, l, u); const float* sp = d.src + (size_t)(d.k0 + k) * d.ldsrc + d.c0 + cg8;
.LBB0_377:
	v_readlane_b32 s4, v255, 8
	v_readlane_b32 s5, v255, 9
	s_nop 2
	s_load_dword s26, s[4:5], 0x0
	s_waitcnt lgkmcnt(0)
	v_readlane_b32 s21, v254, 59
	v_readlane_b32 s51, v255, 16
	v_readfirstlane_b32 s20, v245
	s_nop 1
	s_cmp_lg_u32 s51, 0
	s_cbranch_scc1 .Lwp0_done
	v_and_b32_e32 v0, 63, v245
	v_readlane_b32 s4, v254, 33
	v_readlane_b32 s5, v254, 34
	v_readlane_b32 s6, v254, 57
	v_readlane_b32 s7, v254, 58
	v_readlane_b32 s8, v253, 4
	v_readlane_b32 s9, v253, 5
	v_readlane_b32 s10, v253, 6
	v_readlane_b32 s11, v253, 7
	v_readlane_b32 s12, v254, 60
	v_readlane_b32 s13, v254, 61
	v_readlane_b32 s14, v254, 39
	v_readlane_b32 s15, v254, 40
	v_readlane_b32 s16, v254, 43
	v_readlane_b32 s17, v254, 44
	v_readlane_b32 s18, v255, 0
	v_readlane_b32 s19, v255, 1
	s_lshr_b32 s20, s20, 6
	s_lshl_b32 s31, s20, 14
	s_mul_i32 s0, s51, 0xa20000
	s_add_u32 s4, s4, s0
	s_addc_u32 s5, s5, 0
	s_lshl_b32 s0, s51, 22
	s_add_u32 s6, s6, s0
	s_addc_u32 s7, s7, 0
	s_mul_i32 s0, s51, 0xb00000
	s_add_u32 s8, s8, s0
	s_addc_u32 s9, s9, 0
	s_add_u32 s10, s10, s0
	s_addc_u32 s11, s11, 0
	s_add_u32 s12, s12, s0
	s_addc_u32 s13, s13, 0
	s_lshl_b32 s0, s51, 18
	s_add_u32 s14, s14, s0
	s_addc_u32 s15, s15, 0
	s_add_u32 s16, s16, s0
	s_addc_u32 s17, s17, 0
	v_lshrrev_b32_e32 v1, 4, v0
	v_and_b32_e32 v22, 15, v0
	v_xor_b32_e32 v2, 0, v22
	v_lshlrev_b32_e32 v2, 4, v2
	v_xor_b32_e32 v3, 1, v22
	v_lshlrev_b32_e32 v3, 4, v3
	v_xor_b32_e32 v4, 2, v22
	v_lshlrev_b32_e32 v4, 4, v4
	v_xor_b32_e32 v5, 3, v22
	v_lshlrev_b32_e32 v5, 4, v5
	v_xor_b32_e32 v6, 4, v22
	v_lshlrev_b32_e32 v6, 4, v6
	v_xor_b32_e32 v7, 5, v22
	v_lshlrev_b32_e32 v7, 4, v7
	v_xor_b32_e32 v8, 6, v22
	v_lshlrev_b32_e32 v8, 4, v8
	v_xor_b32_e32 v9, 7, v22
	v_lshlrev_b32_e32 v9, 4, v9
	v_lshrrev_b32_e32 v10, 3, v0
	v_and_b32_e32 v11, 7, v0
	v_lshrrev_b32_e32 v22, 2, v10
	v_and_b32_e32 v23, 3, v10
	v_lshlrev_b32_e32 v23, 2, v23
	v_lshl_add_u32 v23, v11, 11, v23
	v_add_u32_e32 v23, s31, v23
	v_add_u32_e32 v12, 0, v22
	v_xor_b32_e32 v12, v12, v11
	v_lshl_add_u32 v12, v12, 4, v23
	v_add_u32_e32 v13, 2, v22
	v_xor_b32_e32 v13, v13, v11
	v_lshl_add_u32 v13, v13, 4, v23
	v_add_u32_e32 v14, 4, v22
	v_xor_b32_e32 v14, v14, v11
	v_lshl_add_u32 v14, v14, 4, v23
	v_add_u32_e32 v15, 6, v22
	v_xor_b32_e32 v15, v15, v11
	v_lshl_add_u32 v15, v15, 4, v23
	v_add_u32_e32 v16, 8, v22
	v_xor_b32_e32 v16, v16, v11
	v_lshl_add_u32 v16, v16, 4, v23
	v_add_u32_e32 v17, 10, v22
	v_xor_b32_e32 v17, v17, v11
	v_lshl_add_u32 v17, v17, 4, v23
	v_add_u32_e32 v18, 12, v22
	v_xor_b32_e32 v18, v18, v11
	v_lshl_add_u32 v18, v18, 4, v23
	v_add_u32_e32 v19, 14, v22
	v_xor_b32_e32 v19, v19, v11
	v_lshl_add_u32 v19, v19, 4, v23
	s_mul_i32 s27, s20, 256
	s_add_u32 s27, s27, s21

; #define LAS __attribute__((address_space(3)))
; __device__ __forceinline__ unsigned cvtpk(float lo, float hi) { const f32x2 v = (f32x2){lo, hi}; const bf16v2 b = __builtin_convertvector(v, bf16v2); return __builtin_bit_cast(unsigned, b); }
; __device__ void phase_weights(const Params& p, int l, LAS unsigned char* lds) {
;     ...
;         { const int r = tid >> 3, kg = (tid & 7) * 8;
; #pragma unroll
;           for (int j = 0; j < 4; ++j) { const int u = u0 + j * G;
;               if (u < TOT) { const WDesc d = wdesc(p, l, u); const LAS float* Tj = T + j * 4160; u32x4 w;
;                   w.x = cvtpk(Tj[(kg + 0) * 65 + r], Tj[(kg + 1) * 65 + r]); w.y = cvtpk(Tj[(kg + 2) * 65 + r], Tj[(kg + 3) * 65 + r]);
;                   w.z = cvtpk(Tj[(kg + 4) * 65 + r], Tj[(kg + 5) * 65 + r]); w.w = cvtpk(Tj[(kg + 6) * 65 + r], Tj[(kg + 7) * 65 + r]);
;                   *(u32x4*)(d.dst + (size_t)(d.r0 + r) * d.lddst + d.k0 + kg) = w; } } }
;         __syncthreads();
;     }
.Lwp0_s7:
	global_store_dwordx4 v21, v[44:47], s[44:45]
	s_add_u32 s27, s27, 0x800
	s_branch .Lwp0_round
